# idx unit prologue: first k_idx tile DMA issued before the q tile staging (was after the staging barrier)
# baseline (speedup 1.0000x reference)
; #define LAS __attribute__((address_space(3)))
; #define IDX_DMA_K(zo) do { _Pragma("unroll") for (int d0_ = 0; d0_ < 4; ++d0_) attn_body::glds16(kbh + (zo) + d0_ * 16, (unsigned)__builtin_amdgcn_readfirstlane(kdst + d0_ * 1024)); } while (0)
; __device__ __forceinline__ void run(Frame& F, int qword) {
;     ...
;         for (int it = 0; it < 2; ++it) { const int rem = tid + 512 * it, row = rem >> 5, ch = rem & 31;
;             const v4u v = *(const v4u*)(QIH + (tok0 + row) * 256 + ch * 8);
;             *(LAS v4u*)(lds + row * QROW + ch * 16) = v; }
;         const f32x4 w4 = *(const f32x4*)(WI + (tok0 + r32) * 4);
;         __syncthreads();
;         unsigned sc[8][16];
;         const bf16* kbh = KIH + ((size_t)b * SEQ + r32) * 64 + hi * 8;
;         const LAS unsigned char* kbuf = lds + KBUF_OFF + wid * 8192 + lane * 16;
;         const unsigned kdst = (unsigned)(uintptr_t)(lds + KBUF_OFF + wid * 8192);
;     ...
;         if (widv <= qg) { int zoff = widv * 2048; asm volatile("" : "+v"(zoff)); IDX_DMA_K(zoff); }
.LBB0_956:
	s_waitcnt lgkmcnt(0)
	s_barrier
	ds_read_b32 v0, v134
	s_mov_b64 s[0:1], -1
	s_waitcnt lgkmcnt(0)
	v_readfirstlane_b32 s4, v0
	s_cmpk_gt_u32 s4, 0x3ff
	s_cbranch_scc1 .LBB0_949
	v_sub_co_u32_e32 v0, vcc, s4, v135
	s_lshr_b32 s0, s4, 4
	s_sub_i32 s5, 63, s0
	v_readfirstlane_b32 s0, v0
	s_lshr_b32 s6, s0, 4
	s_and_b64 s[0:1], vcc, exec
	s_cselect_b32 s61, s5, s6
	s_and_b32 s4, s4, 15
	s_lshl_b32 s0, s4, 6
	s_add_i32 s34, s61, s0
	s_lshl_b64 s[0:1], s[34:35], 13
	s_add_u32 s38, s46, s0
	v_mbcnt_lo_u32_b32 v136, -1, 0
	v_mbcnt_hi_u32_b32 v136, -1, v136
	s_addc_u32 s39, s47, s1
	s_or_b32 s63, s61, 7
	s_mov_b32 s62, s93
	v_and_b32_e32 v137, 31, v136
	s_cmp_lt_u32 s61, 8
	s_mov_b64 s[0:1], -1
	s_cbranch_scc1 .LBB0_1290
	v_add_u32_e32 v4, s48, v136
	v_ashrrev_i32_e32 v10, 5, v4
	v_add_u32_e32 v4, 0x200, v4
	s_lshl_b32 s12, s61, 5
	s_lshl_b32 s0, s4, 11
	s_cmp_le_i32 s62, s61
	s_cbranch_scc0 .Lidxp_skip
	v_ashrrev_i32_e32 v240, 5, v136
	v_lshlrev_b32_e32 v240, 3, v240
	v_ashrrev_i32_e32 v241, 31, v240
	v_or_b32_e32 v242, s0, v137
	v_lshlrev_b32_e32 v242, 7, v242
	v_mov_b32_e32 v243, 0
	v_lshl_add_u64 v[242:243], s[26:27], 0, v[242:243]
	v_lshl_add_u64 v[242:243], v[240:241], 1, v[242:243]
	s_lshl_b32 s1, s62, 11
	v_mov_b32_e32 v244, s1
	v_ashrrev_i32_e32 v245, 31, v244
	v_lshl_add_u64 v[244:245], v[244:245], 1, v[242:243]
	s_mov_b32 s1, m0
	s_mov_b32 m0, s50
	s_nop 0
	global_load_lds_dwordx4 v[244:245], off
	v_lshl_add_u64 v[246:247], v[244:245], 0, 32
	s_mov_b32 m0, s58
	s_nop 0
	global_load_lds_dwordx4 v[246:247], off
	v_lshl_add_u64 v[246:247], v[244:245], 0, 64
	s_mov_b32 m0, s59
	s_nop 0
	global_load_lds_dwordx4 v[246:247], off
	v_lshl_add_u64 v[244:245], v[244:245], 0, s[36:37]
	s_mov_b32 m0, s60
	s_nop 0
	global_load_lds_dwordx4 v[244:245], off
	s_mov_b32 m0, s1
.Lidxp_skip:
	v_ashrrev_i32_e32 v12, 5, v4
	s_add_i32 s34, s12, s0
	v_ashrrev_i32_e32 v11, 31, v10
	v_ashrrev_i32_e32 v13, 31, v12
	v_lshlrev_b32_e32 v80, 4, v137
	v_lshl_add_u64 v[2:3], v[10:11], 0, s[34:35]
	v_lshl_add_u64 v[4:5], v[12:13], 0, s[34:35]
	v_lshl_add_u64 v[0:1], s[24:25], 0, v[80:81]
	v_lshlrev_b64 v[2:3], 9, v[2:3]
	v_lshlrev_b64 v[4:5], 9, v[4:5]
	v_lshl_add_u64 v[2:3], v[0:1], 0, v[2:3]
	v_lshl_add_u64 v[0:1], v[0:1], 0, v[4:5]
	global_load_dwordx4 v[2:5], v[2:3], off
	s_nop 0
	global_load_dwordx4 v[6:9], v[0:1], off
	v_add_u32_e32 v0, 0, v80
	v_or_b32_e32 v80, s34, v137
	v_lshl_add_u64 v[14:15], v[80:81], 4, s[30:31]
	global_load_dwordx4 v[64:67], v[14:15], off
	v_ashrrev_i32_e32 v1, 5, v136
	v_or_b32_e32 v16, s0, v137
	v_lshlrev_b32_e32 v14, 3, v1
	v_mad_u64_u32 v[10:11], s[0:1], v10, s55, v[0:1]
	s_cmp_le_i32 s62, s61
	v_mad_u64_u32 v[12:13], s[0:1], v12, s55, v[0:1]
	v_lshlrev_b32_e32 v80, 7, v16
	v_ashrrev_i32_e32 v15, 31, v14
	s_cselect_b64 s[0:1], -1, 0
	v_lshl_add_u64 v[16:17], s[26:27], 0, v[80:81]
	s_and_b64 vcc, exec, s[0:1]
	v_lshl_add_u64 v[82:83], v[14:15], 1, v[16:17]
	s_waitcnt vmcnt(2)
	ds_write_b128 v10, v[2:5]
	s_waitcnt vmcnt(1)
	ds_write_b128 v12, v[6:9]
	s_waitcnt lgkmcnt(0)
	s_barrier
